# gate phase v2: two rows interleaved per step, exp of +t and -t from one product
# baseline (speedup 1.0000x reference)
; #define LAS __attribute__((address_space(3)))
; DI float logsig16(float z) { return (fminf(z, 0.f) - __logf(1.0f + __expf(-fabsf(z)))) * (1.0f / 16.0f); }
; DI void gla_gate_phase(const Params& P, LAS unsigned char* lds, int lj) {
;     ...
;   float wf[16], wb[16];
; #pragma unroll
;   for (int j = 0; j < 16; ++j) { wf[j] = Wf[j * 512 + col]; wb[j] = Wb[j * 512 + col]; }
;   const float bf_ = P.in[9][(size_t)lj * 512 + col], bb_ = P.in[11][(size_t)lj * 512 + col];
;   LAS float* zL = (LAS float*)lds;
;   for (int item = blockIdx.x; item < 512; item += gridDim.x) {
;     __syncthreads();
;     { const int row = tid >> 3, part = tid & 7; *(LAS f32x4*)(zL + row * 32 + part * 4) = *(const f32x4*)(zbuf + ((size_t)item * 64 + row) * 32 + part * 4); }
;     __syncthreads();
;     float lsb[64]; float totb = 0.f;
; #pragma unroll
;     for (int i = 0; i < 64; ++i) {
;       float z = bb_;
; #pragma unroll
;       for (int j4 = 0; j4 < 4; ++j4) { const f32x4 zz = *(const LAS f32x4*)(zL + i * 32 + 16 + j4 * 4); z += zz[0] * wb[j4 * 4] + zz[1] * wb[j4 * 4 + 1] + zz[2] * wb[j4 * 4 + 2] + zz[3] * wb[j4 * 4 + 3]; }
;       lsb[i] = logsig16(z); totb += lsb[i];
;     }
.LBB0_178:
	v_readlane_b32 s0, v253, 46
	v_readlane_b32 s1, v253, 47
	v_readlane_b32 s20, v253, 52
	v_mov_b32_e32 v2, v220
	s_andn2_b64 vcc, exec, s[0:1]
	v_readlane_b32 s21, v253, 53
	s_movk_i32 s29, 0x4000
	s_movk_i32 s34, 0x6000
	s_mov_b32 s61, 0x800000
	s_mov_b32 s16, 0xbfb8aa3b
	s_movk_i32 s52, 0x1000
	s_movk_i32 s53, 0x3000
	s_movk_i32 s54, 0x7000
	s_mov_b32 s55, 0x3f317217
	s_mov_b32 s56, 0x7f800000
	s_mov_b32 s57, 0x3d800000
	s_mov_b32 s89, 0x2e000
	s_mov_b32 s17, 0x3a000
	s_mov_b32 s28, 0x3c000
	s_mov_b64 s[90:91], 0x48000
	s_mov_b64 s[92:93], 0x3000
	s_mov_b64 s[82:83], 0x4800
	s_mov_b64 s[84:85], 0x6000
	s_mov_b64 s[86:87], 0x7800
	s_mov_b64 s[62:63], 0x9000
	s_mov_b64 s[72:73], 0xa800
	s_mov_b64 s[96:97], 0xc000
	s_mov_b64 s[74:75], 0xd800
	s_mov_b64 s[66:67], 0xf000
	s_mov_b64 s[76:77], 0x5800
	s_mov_b32 s70, 0x34000
	s_cbranch_vccnz .LBB0_181
	v_readlane_b32 s18, v255, 12
	v_readlane_b32 s36, v254, 39
	v_readlane_b32 s37, v254, 40
	v_readlane_b32 s40, v254, 43
	v_readlane_b32 s41, v254, 44
	v_readlane_b32 s38, v254, 41
	v_readlane_b32 s39, v254, 42
	v_readlane_b32 s46, v254, 45
	v_readlane_b32 s47, v254, 46
	s_mov_b32 s16, 0xbfb8aa3b
	s_mov_b32 s55, 0x3f317217
	s_mov_b32 s57, 0x3d800000
	s_lshl_b32 s19, s18, 15
	s_add_u32 s36, s36, s19
	s_addc_u32 s37, s37, 0
	s_add_u32 s40, s40, s19
	s_addc_u32 s41, s41, 0
	s_lshl_b32 s19, s18, 11
	s_add_u32 s38, s38, s19
	s_addc_u32 s39, s39, 0
	s_add_u32 s46, s46, s19
	s_addc_u32 s47, s47, 0
	v_lshlrev_b32_e32 v36, 2, v220
	v_lshlrev_b32_e32 v37, 1, v220
	v_lshlrev_b32_e32 v48, 4, v220
	global_load_dword v2, v36, s[36:37]
	global_load_dword v18, v36, s[40:41]
	s_add_u32 s36, s36, 0x800
	s_addc_u32 s37, s37, 0
	s_add_u32 s40, s40, 0x800
	s_addc_u32 s41, s41, 0
	global_load_dword v3, v36, s[36:37]
	global_load_dword v19, v36, s[40:41]
	s_add_u32 s36, s36, 0x800
	s_addc_u32 s37, s37, 0
	s_add_u32 s40, s40, 0x800
	s_addc_u32 s41, s41, 0
	global_load_dword v4, v36, s[36:37]
	global_load_dword v20, v36, s[40:41]
	s_add_u32 s36, s36, 0x800
	s_addc_u32 s37, s37, 0
	s_add_u32 s40, s40, 0x800
	s_addc_u32 s41, s41, 0
	global_load_dword v5, v36, s[36:37]
	global_load_dword v21, v36, s[40:41]
	s_add_u32 s36, s36, 0x800
	s_addc_u32 s37, s37, 0
	s_add_u32 s40, s40, 0x800
	s_addc_u32 s41, s41, 0
	global_load_dword v6, v36, s[36:37]
	global_load_dword v22, v36, s[40:41]
	s_add_u32 s36, s36, 0x800
	s_addc_u32 s37, s37, 0
	s_add_u32 s40, s40, 0x800
	s_addc_u32 s41, s41, 0
	global_load_dword v7, v36, s[36:37]
	global_load_dword v23, v36, s[40:41]
	s_add_u32 s36, s36, 0x800
	s_addc_u32 s37, s37, 0
	s_add_u32 s40, s40, 0x800
	s_addc_u32 s41, s41, 0
	global_load_dword v8, v36, s[36:37]
	global_load_dword v24, v36, s[40:41]
	s_add_u32 s36, s36, 0x800
	s_addc_u32 s37, s37, 0
	s_add_u32 s40, s40, 0x800
	s_addc_u32 s41, s41, 0
	global_load_dword v9, v36, s[36:37]
	global_load_dword v25, v36, s[40:41]
	s_add_u32 s36, s36, 0x800
	s_addc_u32 s37, s37, 0
	s_add_u32 s40, s40, 0x800
	s_addc_u32 s41, s41, 0
	global_load_dword v10, v36, s[36:37]
	global_load_dword v26, v36, s[40:41]
	s_add_u32 s36, s36, 0x800
	s_addc_u32 s37, s37, 0
	s_add_u32 s40, s40, 0x800
	s_addc_u32 s41, s41, 0
	global_load_dword v11, v36, s[36:37]
	global_load_dword v27, v36, s[40:41]
	s_add_u32 s36, s36, 0x800
	s_addc_u32 s37, s37, 0
	s_add_u32 s40, s40, 0x800
	s_addc_u32 s41, s41, 0
	global_load_dword v12, v36, s[36:37]
	global_load_dword v28, v36, s[40:41]
	s_add_u32 s36, s36, 0x800
	s_addc_u32 s37, s37, 0
	s_add_u32 s40, s40, 0x800
	s_addc_u32 s41, s41, 0
	global_load_dword v13, v36, s[36:37]
	global_load_dword v29, v36, s[40:41]
	s_add_u32 s36, s36, 0x800
	s_addc_u32 s37, s37, 0
	s_add_u32 s40, s40, 0x800
	s_addc_u32 s41, s41, 0
	global_load_dword v14, v36, s[36:37]
	global_load_dword v30, v36, s[40:41]
	s_add_u32 s36, s36, 0x800
	s_addc_u32 s37, s37, 0
	s_add_u32 s40, s40, 0x800
	s_addc_u32 s41, s41, 0
	global_load_dword v15, v36, s[36:37]
	global_load_dword v31, v36, s[40:41]
	s_add_u32 s36, s36, 0x800
	s_addc_u32 s37, s37, 0
	s_add_u32 s40, s40, 0x800
	s_addc_u32 s41, s41, 0
	global_load_dword v16, v36, s[36:37]
	global_load_dword v32, v36, s[40:41]
	s_add_u32 s36, s36, 0x800
	s_addc_u32 s37, s37, 0
	s_add_u32 s40, s40, 0x800
	s_addc_u32 s41, s41, 0
	global_load_dword v17, v36, s[36:37]
	global_load_dword v33, v36, s[40:41]
	global_load_dword v34, v36, s[38:39]
	global_load_dword v35, v36, s[46:47]
	v_mov_b32_e32 v38, v37
	v_add_u32_e32 v39, 6144, v37
	v_add_u32_e32 v40, 12288, v37
	v_add_u32_e32 v41, 18432, v37
	v_add_u32_e32 v42, 24576, v37
	v_add_u32_e32 v43, 30720, v37
	v_add_u32_e32 v44, 36864, v37
	v_add_u32_e32 v45, 43008, v37
	v_add_u32_e32 v46, 0x1000, v37
	s_mov_b32 s42, s60
.Lgt_item:
	s_waitcnt vmcnt(0) lgkmcnt(0)
	s_barrier
	s_lshl_b32 s0, s42, 13
	s_add_u32 s44, s6, s0
	s_addc_u32 s45, s7, 0
	s_add_u32 s44, s44, 0x900000
	s_addc_u32 s45, s45, 0
	global_load_dwordx4 v[116:119], v48, s[44:45]
	s_mul_i32 s0, s42, 0x60000
	s_add_u32 s46, s6, s0
	s_addc_u32 s47, s7, 0
	s_add_u32 s46, s46, 0x9a00000
	s_addc_u32 s47, s47, 0
	s_lshl_b32 s0, s42, 16
	s_add_u32 s48, s6, s0
	s_addc_u32 s49, s7, 0
	s_add_u32 s48, s48, 0x5a00000
	s_addc_u32 s49, s49, 0
	s_add_u32 s50, s48, 0x2000000
	s_addc_u32 s51, s49, 0
	global_load_ushort v52, v38, s[46:47]
	global_load_ushort v60, v38, s[46:47] offset:1024
	global_load_ushort v53, v39, s[46:47]
	global_load_ushort v61, v39, s[46:47] offset:1024
	global_load_ushort v54, v40, s[46:47]
	global_load_ushort v62, v40, s[46:47] offset:1024
	global_load_ushort v55, v41, s[46:47]
	global_load_ushort v63, v41, s[46:47] offset:1024
	global_load_ushort v56, v42, s[46:47]
	global_load_ushort v64, v42, s[46:47] offset:1024
	global_load_ushort v57, v43, s[46:47]
	global_load_ushort v65, v43, s[46:47] offset:1024
	global_load_ushort v58, v44, s[46:47]
	global_load_ushort v66, v44, s[46:47] offset:1024
	global_load_ushort v59, v45, s[46:47]
	global_load_ushort v67, v45, s[46:47] offset:1024
	s_waitcnt vmcnt(16)
	ds_write_b128 v48, v[116:119]
	s_waitcnt lgkmcnt(0)
	s_barrier
	v_mov_b32_e32 v130, 0
	v_mov_b32_e32 v49, 0
	v_add_u32_e32 v50, 0x2000, v36
	ds_read_b128 v[84:87], v49 offset:64
	ds_read_b128 v[88:91], v49 offset:80
	ds_read_b128 v[92:95], v49 offset:96
	ds_read_b128 v[96:99], v49 offset:112
	ds_read_b128 v[100:103], v49 offset:192
	ds_read_b128 v[104:107], v49 offset:208
	ds_read_b128 v[108:111], v49 offset:224
	ds_read_b128 v[112:115], v49 offset:240
	s_mov_b32 s43, 0
; #define LAS __attribute__((address_space(3)))
; DI float logsig16(float z) { return (fminf(z, 0.f) - __logf(1.0f + __expf(-fabsf(z)))) * (1.0f / 16.0f); }
; DI void gla_gate_phase(const Params& P, LAS unsigned char* lds, int lj) {
;     ...
;     float lsb[64]; float totb = 0.f;
; #pragma unroll
;     for (int i = 0; i < 64; ++i) {
;       float z = bb_;
; #pragma unroll
;       for (int j4 = 0; j4 < 4; ++j4) { const f32x4 zz = *(const LAS f32x4*)(zL + i * 32 + 16 + j4 * 4); z += zz[0] * wb[j4 * 4] + zz[1] * wb[j4 * 4 + 1] + zz[2] * wb[j4 * 4 + 2] + zz[3] * wb[j4 * 4 + 3]; }
;       lsb[i] = logsig16(z); totb += lsb[i];
;     }
.Lgt_pre:
	s_waitcnt lgkmcnt(0)
	v_mul_f32_e32 v120, v19, v85
	v_mul_f32_e32 v136, v19, v101
	v_fmac_f32_e32 v120, v18, v84
	v_fmac_f32_e32 v136, v18, v100
	v_fmac_f32_e32 v120, v20, v86
	v_fmac_f32_e32 v136, v20, v102
	v_fmac_f32_e32 v120, v21, v87
	v_fmac_f32_e32 v136, v21, v103
	v_add_f32_e32 v124, v35, v120
	v_add_f32_e32 v140, v35, v136
	v_mul_f32_e32 v120, v23, v89
	v_mul_f32_e32 v136, v23, v105
	v_fmac_f32_e32 v120, v22, v88
	v_fmac_f32_e32 v136, v22, v104
	v_fmac_f32_e32 v120, v24, v90
	v_fmac_f32_e32 v136, v24, v106
	v_fmac_f32_e32 v120, v25, v91
	v_fmac_f32_e32 v136, v25, v107
	v_add_f32_e32 v124, v124, v120
	v_add_f32_e32 v140, v140, v136
	v_mul_f32_e32 v120, v27, v93
	v_mul_f32_e32 v136, v27, v109
	v_fmac_f32_e32 v120, v26, v92
	v_fmac_f32_e32 v136, v26, v108
	v_fmac_f32_e32 v120, v28, v94
	v_fmac_f32_e32 v136, v28, v110
	v_fmac_f32_e32 v120, v29, v95
	v_fmac_f32_e32 v136, v29, v111
	v_add_f32_e32 v124, v124, v120
	v_add_f32_e32 v140, v140, v136
	v_mul_f32_e32 v120, v31, v97
	v_mul_f32_e32 v136, v31, v113
	v_fmac_f32_e32 v120, v30, v96
	v_fmac_f32_e32 v136, v30, v112
	v_fmac_f32_e32 v120, v32, v98
	v_fmac_f32_e32 v136, v32, v114
	v_fmac_f32_e32 v120, v33, v99
	v_fmac_f32_e32 v136, v33, v115
	v_add_f32_e32 v124, v124, v120
	v_add_f32_e32 v140, v140, v136
	ds_read_b128 v[84:87], v49 offset:320
	ds_read_b128 v[88:91], v49 offset:336
	ds_read_b128 v[92:95], v49 offset:352
	ds_read_b128 v[96:99], v49 offset:368
	ds_read_b128 v[100:103], v49 offset:448
	ds_read_b128 v[104:107], v49 offset:464
	ds_read_b128 v[108:111], v49 offset:480
	ds_read_b128 v[112:115], v49 offset:496
	v_min_f32_e32 v121, 0, v124
	v_min_f32_e32 v137, 0, v140
	v_mul_f32_e64 v122, |v124|, s16
	v_mul_f32_e64 v138, |v140|, s16
	v_exp_f32_e32 v122, v122
	v_exp_f32_e32 v138, v138
	v_add_f32_e32 v122, 1.0, v122
	v_add_f32_e32 v138, 1.0, v138
	v_log_f32_e32 v122, v122
	v_log_f32_e32 v138, v138
	v_mul_f32_e32 v123, 0x3f317217, v122
	v_mul_f32_e32 v139, 0x3f317217, v138
	v_fma_f32 v123, v122, s55, -v123
	v_fma_f32 v139, v138, s55, -v139
	v_fmac_f32_e32 v123, 0x3377d1cf, v122
	v_fmac_f32_e32 v139, 0x3377d1cf, v138
	v_fmac_f32_e32 v123, 0x3f317217, v122
	v_fmac_f32_e32 v139, 0x3f317217, v138
	v_sub_f32_e32 v124, v121, v123
	v_sub_f32_e32 v140, v137, v139
	v_mul_f32_e32 v134, 0x3d800000, v124
	v_mul_f32_e32 v135, 0x3d800000, v140
	ds_write_b32 v50, v134 offset:0
	ds_write_b32 v50, v135 offset:2048
	v_add_f32_e32 v130, v130, v134
	v_add_f32_e32 v130, v130, v135
	s_waitcnt lgkmcnt(0)
	v_mul_f32_e32 v120, v19, v85
	v_mul_f32_e32 v136, v19, v101
	v_fmac_f32_e32 v120, v18, v84
	v_fmac_f32_e32 v136, v18, v100
	v_fmac_f32_e32 v120, v20, v86
	v_fmac_f32_e32 v136, v20, v102
	v_fmac_f32_e32 v120, v21, v87
	v_fmac_f32_e32 v136, v21, v103
	v_add_f32_e32 v124, v35, v120
	v_add_f32_e32 v140, v35, v136
	v_mul_f32_e32 v120, v23, v89
	v_mul_f32_e32 v136, v23, v105
	v_fmac_f32_e32 v120, v22, v88
	v_fmac_f32_e32 v136, v22, v104
	v_fmac_f32_e32 v120, v24, v90
	v_fmac_f32_e32 v136, v24, v106
	v_fmac_f32_e32 v120, v25, v91
	v_fmac_f32_e32 v136, v25, v107
	v_add_f32_e32 v124, v124, v120
	v_add_f32_e32 v140, v140, v136
	v_mul_f32_e32 v120, v27, v93
	v_mul_f32_e32 v136, v27, v109
	v_fmac_f32_e32 v120, v26, v92
	v_fmac_f32_e32 v136, v26, v108
	v_fmac_f32_e32 v120, v28, v94
	v_fmac_f32_e32 v136, v28, v110
	v_fmac_f32_e32 v120, v29, v95
	v_fmac_f32_e32 v136, v29, v111
	v_add_f32_e32 v124, v124, v120
	v_add_f32_e32 v140, v140, v136
	v_mul_f32_e32 v120, v31, v97
	v_mul_f32_e32 v136, v31, v113
	v_fmac_f32_e32 v120, v30, v96
	v_fmac_f32_e32 v136, v30, v112
	v_fmac_f32_e32 v120, v32, v98
	v_fmac_f32_e32 v136, v32, v114
	v_fmac_f32_e32 v120, v33, v99
	v_fmac_f32_e32 v136, v33, v115
	v_add_f32_e32 v124, v124, v120
	v_add_f32_e32 v140, v140, v136
	ds_read_b128 v[84:87], v49 offset:576
	ds_read_b128 v[88:91], v49 offset:592
	ds_read_b128 v[92:95], v49 offset:608
	ds_read_b128 v[96:99], v49 offset:624
	ds_read_b128 v[100:103], v49 offset:704
	ds_read_b128 v[104:107], v49 offset:720
	ds_read_b128 v[108:111], v49 offset:736
	ds_read_b128 v[112:115], v49 offset:752
	v_min_f32_e32 v121, 0, v124
	v_min_f32_e32 v137, 0, v140
	v_mul_f32_e64 v122, |v124|, s16
	v_mul_f32_e64 v138, |v140|, s16
	v_exp_f32_e32 v122, v122
	v_exp_f32_e32 v138, v138
	v_add_f32_e32 v122, 1.0, v122
	v_add_f32_e32 v138, 1.0, v138
	v_log_f32_e32 v122, v122
	v_log_f32_e32 v138, v138
	v_mul_f32_e32 v123, 0x3f317217, v122
	v_mul_f32_e32 v139, 0x3f317217, v138
	v_fma_f32 v123, v122, s55, -v123
	v_fma_f32 v139, v138, s55, -v139
	v_fmac_f32_e32 v123, 0x3377d1cf, v122
	v_fmac_f32_e32 v139, 0x3377d1cf, v138
	v_fmac_f32_e32 v123, 0x3f317217, v122
	v_fmac_f32_e32 v139, 0x3f317217, v138
	v_sub_f32_e32 v124, v121, v123
	v_sub_f32_e32 v140, v137, v139
	v_mul_f32_e32 v134, 0x3d800000, v124
	v_mul_f32_e32 v135, 0x3d800000, v140
	ds_write_b32 v50, v134 offset:4096
	ds_write_b32 v50, v135 offset:6144
	v_add_f32_e32 v130, v130, v134
	v_add_f32_e32 v130, v130, v135
	s_waitcnt lgkmcnt(0)
; #define LAS __attribute__((address_space(3)))
; DI float logsig16(float z) { return (fminf(z, 0.f) - __logf(1.0f + __expf(-fabsf(z)))) * (1.0f / 16.0f); }
; DI void gla_gate_phase(const Params& P, LAS unsigned char* lds, int lj) {
;     ...
;     float lsb[64]; float totb = 0.f;
; #pragma unroll
;     for (int i = 0; i < 64; ++i) {
;       float z = bb_;
; #pragma unroll
;       for (int j4 = 0; j4 < 4; ++j4) { const f32x4 zz = *(const LAS f32x4*)(zL + i * 32 + 16 + j4 * 4); z += zz[0] * wb[j4 * 4] + zz[1] * wb[j4 * 4 + 1] + zz[2] * wb[j4 * 4 + 2] + zz[3] * wb[j4 * 4 + 3]; }
;       lsb[i] = logsig16(z); totb += lsb[i];
;     }
;     float runf = 0.f, runb = 0.f;
; #pragma unroll
;     for (int ib = 0; ib < 4; ++ib) {
;       bf16_t qraw[16], kraw[16];
; #pragma unroll
;       for (int ii = 0; ii < 16; ++ii) { const bf16_t* pr = proj + ((size_t)item * 64 + ib * 16 + ii) * 3072 + col; qraw[ii] = pr[0]; kraw[ii] = pr[512]; }
	v_mul_f32_e32 v120, v19, v85
	v_mul_f32_e32 v136, v19, v101
	v_fmac_f32_e32 v120, v18, v84
	v_fmac_f32_e32 v136, v18, v100
	v_fmac_f32_e32 v120, v20, v86
	v_fmac_f32_e32 v136, v20, v102
	v_fmac_f32_e32 v120, v21, v87
	v_fmac_f32_e32 v136, v21, v103
	v_add_f32_e32 v124, v35, v120
	v_add_f32_e32 v140, v35, v136
	v_mul_f32_e32 v120, v23, v89
	v_mul_f32_e32 v136, v23, v105
	v_fmac_f32_e32 v120, v22, v88
	v_fmac_f32_e32 v136, v22, v104
	v_fmac_f32_e32 v120, v24, v90
	v_fmac_f32_e32 v136, v24, v106
	v_fmac_f32_e32 v120, v25, v91
	v_fmac_f32_e32 v136, v25, v107
	v_add_f32_e32 v124, v124, v120
	v_add_f32_e32 v140, v140, v136
	v_mul_f32_e32 v120, v27, v93
	v_mul_f32_e32 v136, v27, v109
	v_fmac_f32_e32 v120, v26, v92
	v_fmac_f32_e32 v136, v26, v108
	v_fmac_f32_e32 v120, v28, v94
	v_fmac_f32_e32 v136, v28, v110
	v_fmac_f32_e32 v120, v29, v95
	v_fmac_f32_e32 v136, v29, v111
	v_add_f32_e32 v124, v124, v120
	v_add_f32_e32 v140, v140, v136
	v_mul_f32_e32 v120, v31, v97
	v_mul_f32_e32 v136, v31, v113
	v_fmac_f32_e32 v120, v30, v96
	v_fmac_f32_e32 v136, v30, v112
	v_fmac_f32_e32 v120, v32, v98
	v_fmac_f32_e32 v136, v32, v114
	v_fmac_f32_e32 v120, v33, v99
	v_fmac_f32_e32 v136, v33, v115
	v_add_f32_e32 v124, v124, v120
	v_add_f32_e32 v140, v140, v136
	ds_read_b128 v[84:87], v49 offset:832
	ds_read_b128 v[88:91], v49 offset:848
	ds_read_b128 v[92:95], v49 offset:864
	ds_read_b128 v[96:99], v49 offset:880
	ds_read_b128 v[100:103], v49 offset:960
	ds_read_b128 v[104:107], v49 offset:976
	ds_read_b128 v[108:111], v49 offset:992
	ds_read_b128 v[112:115], v49 offset:1008
	v_min_f32_e32 v121, 0, v124
	v_min_f32_e32 v137, 0, v140
	v_mul_f32_e64 v122, |v124|, s16
	v_mul_f32_e64 v138, |v140|, s16
	v_exp_f32_e32 v122, v122
	v_exp_f32_e32 v138, v138
	v_add_f32_e32 v122, 1.0, v122
	v_add_f32_e32 v138, 1.0, v138
	v_log_f32_e32 v122, v122
	v_log_f32_e32 v138, v138
	v_mul_f32_e32 v123, 0x3f317217, v122
	v_mul_f32_e32 v139, 0x3f317217, v138
	v_fma_f32 v123, v122, s55, -v123
	v_fma_f32 v139, v138, s55, -v139
	v_fmac_f32_e32 v123, 0x3377d1cf, v122
	v_fmac_f32_e32 v139, 0x3377d1cf, v138
	v_fmac_f32_e32 v123, 0x3f317217, v122
	v_fmac_f32_e32 v139, 0x3f317217, v138
	v_sub_f32_e32 v124, v121, v123
	v_sub_f32_e32 v140, v137, v139
	v_mul_f32_e32 v134, 0x3d800000, v124
	v_mul_f32_e32 v135, 0x3d800000, v140
	ds_write_b32 v50, v134 offset:8192
	ds_write_b32 v50, v135 offset:10240
	v_add_f32_e32 v130, v130, v134
	v_add_f32_e32 v130, v130, v135
	s_waitcnt lgkmcnt(0)
	v_mul_f32_e32 v120, v19, v85
	v_mul_f32_e32 v136, v19, v101
	v_fmac_f32_e32 v120, v18, v84
	v_fmac_f32_e32 v136, v18, v100
	v_fmac_f32_e32 v120, v20, v86
	v_fmac_f32_e32 v136, v20, v102
	v_fmac_f32_e32 v120, v21, v87
	v_fmac_f32_e32 v136, v21, v103
	v_add_f32_e32 v124, v35, v120
	v_add_f32_e32 v140, v35, v136
	v_mul_f32_e32 v120, v23, v89
	v_mul_f32_e32 v136, v23, v105
	v_fmac_f32_e32 v120, v22, v88
	v_fmac_f32_e32 v136, v22, v104
	v_fmac_f32_e32 v120, v24, v90
	v_fmac_f32_e32 v136, v24, v106
	v_fmac_f32_e32 v120, v25, v91
	v_fmac_f32_e32 v136, v25, v107
	v_add_f32_e32 v124, v124, v120
	v_add_f32_e32 v140, v140, v136
	v_mul_f32_e32 v120, v27, v93
	v_mul_f32_e32 v136, v27, v109
	v_fmac_f32_e32 v120, v26, v92
	v_fmac_f32_e32 v136, v26, v108
	v_fmac_f32_e32 v120, v28, v94
	v_fmac_f32_e32 v136, v28, v110
	v_fmac_f32_e32 v120, v29, v95
	v_fmac_f32_e32 v136, v29, v111
	v_add_f32_e32 v124, v124, v120
	v_add_f32_e32 v140, v140, v136
	v_mul_f32_e32 v120, v31, v97
	v_mul_f32_e32 v136, v31, v113
	v_fmac_f32_e32 v120, v30, v96
	v_fmac_f32_e32 v136, v30, v112
	v_fmac_f32_e32 v120, v32, v98
	v_fmac_f32_e32 v136, v32, v114
	v_fmac_f32_e32 v120, v33, v99
	v_fmac_f32_e32 v136, v33, v115
	v_add_f32_e32 v124, v124, v120
	v_add_f32_e32 v140, v140, v136
	v_add_u32_e32 v49, 0x400, v49
	ds_read_b128 v[84:87], v49 offset:64
	ds_read_b128 v[88:91], v49 offset:80
	ds_read_b128 v[92:95], v49 offset:96
	ds_read_b128 v[96:99], v49 offset:112
	ds_read_b128 v[100:103], v49 offset:192
	ds_read_b128 v[104:107], v49 offset:208
	ds_read_b128 v[108:111], v49 offset:224
	ds_read_b128 v[112:115], v49 offset:240
	v_min_f32_e32 v121, 0, v124
	v_min_f32_e32 v137, 0, v140
	v_mul_f32_e64 v122, |v124|, s16
	v_mul_f32_e64 v138, |v140|, s16
	v_exp_f32_e32 v122, v122
	v_exp_f32_e32 v138, v138
	v_add_f32_e32 v122, 1.0, v122
	v_add_f32_e32 v138, 1.0, v138
	v_log_f32_e32 v122, v122
	v_log_f32_e32 v138, v138
	v_mul_f32_e32 v123, 0x3f317217, v122
	v_mul_f32_e32 v139, 0x3f317217, v138
	v_fma_f32 v123, v122, s55, -v123
	v_fma_f32 v139, v138, s55, -v139
	v_fmac_f32_e32 v123, 0x3377d1cf, v122
	v_fmac_f32_e32 v139, 0x3377d1cf, v138
	v_fmac_f32_e32 v123, 0x3f317217, v122
	v_fmac_f32_e32 v139, 0x3f317217, v138
	v_sub_f32_e32 v124, v121, v123
	v_sub_f32_e32 v140, v137, v139
	v_mul_f32_e32 v134, 0x3d800000, v124
	v_mul_f32_e32 v135, 0x3d800000, v140
	ds_write_b32 v50, v134 offset:12288
	ds_write_b32 v50, v135 offset:14336
	v_add_f32_e32 v130, v130, v134
	v_add_f32_e32 v130, v130, v135
	v_add_u32_e32 v50, 0x4000, v50
	s_add_i32 s43, s43, 1
	s_cmp_lt_u32 s43, 8
	s_cbranch_scc1 .Lgt_pre
	s_waitcnt lgkmcnt(0)
	v_mov_b32_e32 v128, 0
	v_mov_b32_e32 v129, 0
	v_mov_b32_e32 v49, 0
	v_add_u32_e32 v50, 0x2000, v36
	ds_read_b128 v[84:87], v49 offset:0
	ds_read_b128 v[88:91], v49 offset:16
	ds_read_b128 v[92:95], v49 offset:32
	ds_read_b128 v[96:99], v49 offset:48
	ds_read_b128 v[100:103], v49 offset:128
	ds_read_b128 v[104:107], v49 offset:144
	ds_read_b128 v[108:111], v49 offset:160
	ds_read_b128 v[112:115], v49 offset:176
	s_mov_b32 s43, 0

; #define LAS __attribute__((address_space(3)))
; DI float bf2f(bf16_t v) { return __uint_as_float(((unsigned)v) << 16); }
; DI bf16_t f2bf(float f) { return (bf16_t)(cvt_pk(f, 0.f) & 0xffffu); }
; DI float logsig16(float z) { return (fminf(z, 0.f) - __logf(1.0f + __expf(-fabsf(z)))) * (1.0f / 16.0f); }
; DI void gla_gate_phase(const Params& P, LAS unsigned char* lds, int lj) {
;     ...
;       for (int ii = 0; ii < 16; ++ii) {
;         const int i = ib * 16 + ii;
;         float z = bf_;
; #pragma unroll
;         for (int j4 = 0; j4 < 4; ++j4) { const f32x4 zz = *(const LAS f32x4*)(zL + i * 32 + j4 * 4); z += zz[0] * wf[j4 * 4] + zz[1] * wf[j4 * 4 + 1] + zz[2] * wf[j4 * 4 + 2] + zz[3] * wf[j4 * 4 + 3]; }
;         runf += logsig16(z);
;         const float Bi = totb - runb; runb += lsb[i];
;         const size_t tokrow = (size_t)item * 64 + i;
;         bf16_t* pr = proj + tokrow * 3072 + col;
;         const float q = bf2f(qraw[ii]), k = bf2f(kraw[ii]);
;         pr[0] = f2bf(q * __expf(runf)); pr[512] = f2bf(k * __expf(-runf));
;         QB[tokrow * 512 + col] = f2bf(q * __expf(Bi)); KB[tokrow * 512 + col] = f2bf(k * __expf(-Bi));
;       }
.Lgt_nold:
	s_waitcnt lgkmcnt(0)
	ds_read_b32 v134, v50 offset:0
	ds_read_b32 v135, v50 offset:2048
	v_mul_f32_e32 v120, v3, v85
	v_mul_f32_e32 v136, v3, v101
	v_fmac_f32_e32 v120, v2, v84
	v_fmac_f32_e32 v136, v2, v100
	v_fmac_f32_e32 v120, v4, v86
	v_fmac_f32_e32 v136, v4, v102
	v_fmac_f32_e32 v120, v5, v87
	v_fmac_f32_e32 v136, v5, v103
	v_add_f32_e32 v124, v34, v120
	v_add_f32_e32 v140, v34, v136
	v_mul_f32_e32 v120, v7, v89
	v_mul_f32_e32 v136, v7, v105
	v_fmac_f32_e32 v120, v6, v88
	v_fmac_f32_e32 v136, v6, v104
	v_fmac_f32_e32 v120, v8, v90
	v_fmac_f32_e32 v136, v8, v106
	v_fmac_f32_e32 v120, v9, v91
	v_fmac_f32_e32 v136, v9, v107
	v_add_f32_e32 v124, v124, v120
	v_add_f32_e32 v140, v140, v136
	v_mul_f32_e32 v120, v11, v93
	v_mul_f32_e32 v136, v11, v109
	v_fmac_f32_e32 v120, v10, v92
	v_fmac_f32_e32 v136, v10, v108
	v_fmac_f32_e32 v120, v12, v94
	v_fmac_f32_e32 v136, v12, v110
	v_fmac_f32_e32 v120, v13, v95
	v_fmac_f32_e32 v136, v13, v111
	v_add_f32_e32 v124, v124, v120
	v_add_f32_e32 v140, v140, v136
	v_mul_f32_e32 v120, v15, v97
	v_mul_f32_e32 v136, v15, v113
	v_fmac_f32_e32 v120, v14, v96
	v_fmac_f32_e32 v136, v14, v112
	v_fmac_f32_e32 v120, v16, v98
	v_fmac_f32_e32 v136, v16, v114
	v_fmac_f32_e32 v120, v17, v99
	v_fmac_f32_e32 v136, v17, v115
	v_add_f32_e32 v124, v124, v120
	v_add_f32_e32 v140, v140, v136
	ds_read_b128 v[84:87], v49 offset:256
	ds_read_b128 v[88:91], v49 offset:272
	ds_read_b128 v[92:95], v49 offset:288
	ds_read_b128 v[96:99], v49 offset:304
	ds_read_b128 v[100:103], v49 offset:384
	ds_read_b128 v[104:107], v49 offset:400
	ds_read_b128 v[108:111], v49 offset:416
	ds_read_b128 v[112:115], v49 offset:432
	v_min_f32_e32 v121, 0, v124
	v_min_f32_e32 v137, 0, v140
	v_mul_f32_e64 v122, |v124|, s16
	v_mul_f32_e64 v138, |v140|, s16
	v_exp_f32_e32 v122, v122
	v_exp_f32_e32 v138, v138
	v_add_f32_e32 v122, 1.0, v122
	v_add_f32_e32 v138, 1.0, v138
	v_log_f32_e32 v122, v122
	v_log_f32_e32 v138, v138
	v_mul_f32_e32 v123, 0x3f317217, v122
	v_mul_f32_e32 v139, 0x3f317217, v138
	v_fma_f32 v123, v122, s55, -v123
	v_fma_f32 v139, v138, s55, -v139
	v_fmac_f32_e32 v123, 0x3377d1cf, v122
	v_fmac_f32_e32 v139, 0x3377d1cf, v138
	v_fmac_f32_e32 v123, 0x3f317217, v122
	v_fmac_f32_e32 v139, 0x3f317217, v138
	v_sub_f32_e32 v124, v121, v123
	v_sub_f32_e32 v140, v137, v139
	s_waitcnt lgkmcnt(8)
	v_fma_f32 v144, v124, s57, v128
	v_sub_f32_e32 v127, v130, v129
	v_add_f32_e32 v145, v129, v134
	v_fma_f32 v128, v140, s57, v144
	v_sub_f32_e32 v143, v130, v145
	v_add_f32_e32 v129, v145, v135
	v_mul_f32_e32 v132, 0x3fb8aa3b, v144
	v_mul_f32_e32 v133, 0x3fb8aa3b, v128
	v_exp_f32_e32 v125, v132
	v_exp_f32_e32 v141, v133
	v_exp_f32_e64 v126, -v132
	v_exp_f32_e64 v142, -v133
	v_mul_f32_e32 v132, 0x3fb8aa3b, v127
	v_mul_f32_e32 v133, 0x3fb8aa3b, v143
	v_mul_f32_e32 v125, v125, v68
	v_mul_f32_e32 v141, v141, v69
	v_mul_f32_e32 v126, v126, v76
	v_mul_f32_e32 v142, v142, v77
	v_cvt_pk_bf16_f32 v125, v125, v1
	v_cvt_pk_bf16_f32 v141, v141, v1
	v_cvt_pk_bf16_f32 v126, v126, v1
	v_cvt_pk_bf16_f32 v142, v142, v1
	global_store_short v38, v125, s[46:47]
	global_store_short v39, v141, s[46:47]
	global_store_short v38, v126, s[46:47] offset:1024
	global_store_short v39, v142, s[46:47] offset:1024
	v_exp_f32_e32 v120, v132
	v_exp_f32_e32 v136, v133
	v_exp_f32_e64 v121, -v132
	v_exp_f32_e64 v137, -v133
	v_nop
	v_nop
	v_nop
	v_nop
	v_mul_f32_e32 v120, v120, v68
	v_mul_f32_e32 v136, v136, v69
	v_mul_f32_e32 v121, v121, v76
	v_mul_f32_e32 v137, v137, v77
	v_cvt_pk_bf16_f32 v120, v120, v1
	v_cvt_pk_bf16_f32 v136, v136, v1
	v_cvt_pk_bf16_f32 v121, v121, v1
	v_cvt_pk_bf16_f32 v137, v137, v1
	global_store_short v37, v120, s[48:49]
	global_store_short v37, v136, s[48:49] offset:1024
	global_store_short v37, v121, s[50:51]
	global_store_short v37, v137, s[50:51] offset:1024
	s_waitcnt lgkmcnt(0)
	ds_read_b32 v134, v50 offset:4096
	ds_read_b32 v135, v50 offset:6144
	v_mul_f32_e32 v120, v3, v85
	v_mul_f32_e32 v136, v3, v101
	v_fmac_f32_e32 v120, v2, v84
	v_fmac_f32_e32 v136, v2, v100
	v_fmac_f32_e32 v120, v4, v86
	v_fmac_f32_e32 v136, v4, v102
	v_fmac_f32_e32 v120, v5, v87
	v_fmac_f32_e32 v136, v5, v103
	v_add_f32_e32 v124, v34, v120
	v_add_f32_e32 v140, v34, v136
	v_mul_f32_e32 v120, v7, v89
	v_mul_f32_e32 v136, v7, v105
	v_fmac_f32_e32 v120, v6, v88
	v_fmac_f32_e32 v136, v6, v104
	v_fmac_f32_e32 v120, v8, v90
	v_fmac_f32_e32 v136, v8, v106
	v_fmac_f32_e32 v120, v9, v91
	v_fmac_f32_e32 v136, v9, v107
	v_add_f32_e32 v124, v124, v120
	v_add_f32_e32 v140, v140, v136
	v_mul_f32_e32 v120, v11, v93
	v_mul_f32_e32 v136, v11, v109
	v_fmac_f32_e32 v120, v10, v92
	v_fmac_f32_e32 v136, v10, v108
	v_fmac_f32_e32 v120, v12, v94
	v_fmac_f32_e32 v136, v12, v110
	v_fmac_f32_e32 v120, v13, v95
	v_fmac_f32_e32 v136, v13, v111
	v_add_f32_e32 v124, v124, v120
	v_add_f32_e32 v140, v140, v136
	v_mul_f32_e32 v120, v15, v97
	v_mul_f32_e32 v136, v15, v113
	v_fmac_f32_e32 v120, v14, v96
	v_fmac_f32_e32 v136, v14, v112
	v_fmac_f32_e32 v120, v16, v98
	v_fmac_f32_e32 v136, v16, v114
	v_fmac_f32_e32 v120, v17, v99
	v_fmac_f32_e32 v136, v17, v115
	v_add_f32_e32 v124, v124, v120
	v_add_f32_e32 v140, v140, v136
	ds_read_b128 v[84:87], v49 offset:512
	ds_read_b128 v[88:91], v49 offset:528
	ds_read_b128 v[92:95], v49 offset:544
	ds_read_b128 v[96:99], v49 offset:560
	ds_read_b128 v[100:103], v49 offset:640
	ds_read_b128 v[104:107], v49 offset:656
	ds_read_b128 v[108:111], v49 offset:672
	ds_read_b128 v[112:115], v49 offset:688
	v_min_f32_e32 v121, 0, v124
	v_min_f32_e32 v137, 0, v140
	v_mul_f32_e64 v122, |v124|, s16
	v_mul_f32_e64 v138, |v140|, s16
	v_exp_f32_e32 v122, v122
	v_exp_f32_e32 v138, v138
	v_add_f32_e32 v122, 1.0, v122
	v_add_f32_e32 v138, 1.0, v138
	v_log_f32_e32 v122, v122
	v_log_f32_e32 v138, v138
	v_mul_f32_e32 v123, 0x3f317217, v122
	v_mul_f32_e32 v139, 0x3f317217, v138
	v_fma_f32 v123, v122, s55, -v123
	v_fma_f32 v139, v138, s55, -v139
	v_fmac_f32_e32 v123, 0x3377d1cf, v122
	v_fmac_f32_e32 v139, 0x3377d1cf, v138
	v_fmac_f32_e32 v123, 0x3f317217, v122
	v_fmac_f32_e32 v139, 0x3f317217, v138
	v_sub_f32_e32 v124, v121, v123
	v_sub_f32_e32 v140, v137, v139
	s_waitcnt lgkmcnt(8)
; #define LAS __attribute__((address_space(3)))
; DI float bf2f(bf16_t v) { return __uint_as_float(((unsigned)v) << 16); }
; DI bf16_t f2bf(float f) { return (bf16_t)(cvt_pk(f, 0.f) & 0xffffu); }
; DI float logsig16(float z) { return (fminf(z, 0.f) - __logf(1.0f + __expf(-fabsf(z)))) * (1.0f / 16.0f); }
; DI void gla_gate_phase(const Params& P, LAS unsigned char* lds, int lj) {
;     ...
;       for (int ii = 0; ii < 16; ++ii) {
;         const int i = ib * 16 + ii;
;         float z = bf_;
; #pragma unroll
;         for (int j4 = 0; j4 < 4; ++j4) { const f32x4 zz = *(const LAS f32x4*)(zL + i * 32 + j4 * 4); z += zz[0] * wf[j4 * 4] + zz[1] * wf[j4 * 4 + 1] + zz[2] * wf[j4 * 4 + 2] + zz[3] * wf[j4 * 4 + 3]; }
;         runf += logsig16(z);
;         const float Bi = totb - runb; runb += lsb[i];
;         const size_t tokrow = (size_t)item * 64 + i;
;         bf16_t* pr = proj + tokrow * 3072 + col;
;         const float q = bf2f(qraw[ii]), k = bf2f(kraw[ii]);
;         pr[0] = f2bf(q * __expf(runf)); pr[512] = f2bf(k * __expf(-runf));
;         QB[tokrow * 512 + col] = f2bf(q * __expf(Bi)); KB[tokrow * 512 + col] = f2bf(k * __expf(-Bi));
;       }
	v_fma_f32 v144, v124, s57, v128
	v_sub_f32_e32 v127, v130, v129
	v_add_f32_e32 v145, v129, v134
	v_fma_f32 v128, v140, s57, v144
	v_sub_f32_e32 v143, v130, v145
	v_add_f32_e32 v129, v145, v135
	v_mul_f32_e32 v132, 0x3fb8aa3b, v144
	v_mul_f32_e32 v133, 0x3fb8aa3b, v128
	v_exp_f32_e32 v125, v132
	v_exp_f32_e32 v141, v133
	v_exp_f32_e64 v126, -v132
	v_exp_f32_e64 v142, -v133
	v_mul_f32_e32 v132, 0x3fb8aa3b, v127
	v_mul_f32_e32 v133, 0x3fb8aa3b, v143
	v_mul_f32_e32 v125, v125, v70
	v_mul_f32_e32 v141, v141, v71
	v_mul_f32_e32 v126, v126, v78
	v_mul_f32_e32 v142, v142, v79
	v_cvt_pk_bf16_f32 v125, v125, v1
	v_cvt_pk_bf16_f32 v141, v141, v1
	v_cvt_pk_bf16_f32 v126, v126, v1
	v_cvt_pk_bf16_f32 v142, v142, v1
	global_store_short v40, v125, s[46:47]
	global_store_short v41, v141, s[46:47]
	global_store_short v40, v126, s[46:47] offset:1024
	global_store_short v41, v142, s[46:47] offset:1024
	v_exp_f32_e32 v120, v132
	v_exp_f32_e32 v136, v133
	v_exp_f32_e64 v121, -v132
	v_exp_f32_e64 v137, -v133
	v_nop
	v_nop
	v_nop
	v_nop
	v_mul_f32_e32 v120, v120, v70
	v_mul_f32_e32 v136, v136, v71
	v_mul_f32_e32 v121, v121, v78
	v_mul_f32_e32 v137, v137, v79
	v_cvt_pk_bf16_f32 v120, v120, v1
	v_cvt_pk_bf16_f32 v136, v136, v1
	v_cvt_pk_bf16_f32 v121, v121, v1
	v_cvt_pk_bf16_f32 v137, v137, v1
	global_store_short v37, v120, s[48:49] offset:2048
	global_store_short v37, v136, s[48:49] offset:3072
	global_store_short v37, v121, s[50:51] offset:2048
	global_store_short v37, v137, s[50:51] offset:3072
	s_waitcnt lgkmcnt(0)
	ds_read_b32 v134, v50 offset:8192
	ds_read_b32 v135, v50 offset:10240
	v_mul_f32_e32 v120, v3, v85
	v_mul_f32_e32 v136, v3, v101
	v_fmac_f32_e32 v120, v2, v84
	v_fmac_f32_e32 v136, v2, v100
	v_fmac_f32_e32 v120, v4, v86
	v_fmac_f32_e32 v136, v4, v102
	v_fmac_f32_e32 v120, v5, v87
	v_fmac_f32_e32 v136, v5, v103
	v_add_f32_e32 v124, v34, v120
	v_add_f32_e32 v140, v34, v136
	v_mul_f32_e32 v120, v7, v89
	v_mul_f32_e32 v136, v7, v105
	v_fmac_f32_e32 v120, v6, v88
	v_fmac_f32_e32 v136, v6, v104
	v_fmac_f32_e32 v120, v8, v90
	v_fmac_f32_e32 v136, v8, v106
	v_fmac_f32_e32 v120, v9, v91
	v_fmac_f32_e32 v136, v9, v107
	v_add_f32_e32 v124, v124, v120
	v_add_f32_e32 v140, v140, v136
	v_mul_f32_e32 v120, v11, v93
	v_mul_f32_e32 v136, v11, v109
	v_fmac_f32_e32 v120, v10, v92
	v_fmac_f32_e32 v136, v10, v108
	v_fmac_f32_e32 v120, v12, v94
	v_fmac_f32_e32 v136, v12, v110
	v_fmac_f32_e32 v120, v13, v95
	v_fmac_f32_e32 v136, v13, v111
	v_add_f32_e32 v124, v124, v120
	v_add_f32_e32 v140, v140, v136
	v_mul_f32_e32 v120, v15, v97
	v_mul_f32_e32 v136, v15, v113
	v_fmac_f32_e32 v120, v14, v96
	v_fmac_f32_e32 v136, v14, v112
	v_fmac_f32_e32 v120, v16, v98
	v_fmac_f32_e32 v136, v16, v114
	v_fmac_f32_e32 v120, v17, v99
	v_fmac_f32_e32 v136, v17, v115
	v_add_f32_e32 v124, v124, v120
	v_add_f32_e32 v140, v140, v136
	ds_read_b128 v[84:87], v49 offset:768
	ds_read_b128 v[88:91], v49 offset:784
	ds_read_b128 v[92:95], v49 offset:800
	ds_read_b128 v[96:99], v49 offset:816
	ds_read_b128 v[100:103], v49 offset:896
	ds_read_b128 v[104:107], v49 offset:912
	ds_read_b128 v[108:111], v49 offset:928
	ds_read_b128 v[112:115], v49 offset:944
	v_min_f32_e32 v121, 0, v124
	v_min_f32_e32 v137, 0, v140
	v_mul_f32_e64 v122, |v124|, s16
	v_mul_f32_e64 v138, |v140|, s16
	v_exp_f32_e32 v122, v122
	v_exp_f32_e32 v138, v138
	v_add_f32_e32 v122, 1.0, v122
	v_add_f32_e32 v138, 1.0, v138
	v_log_f32_e32 v122, v122
	v_log_f32_e32 v138, v138
	v_mul_f32_e32 v123, 0x3f317217, v122
	v_mul_f32_e32 v139, 0x3f317217, v138
	v_fma_f32 v123, v122, s55, -v123
	v_fma_f32 v139, v138, s55, -v139
	v_fmac_f32_e32 v123, 0x3377d1cf, v122
	v_fmac_f32_e32 v139, 0x3377d1cf, v138
	v_fmac_f32_e32 v123, 0x3f317217, v122
	v_fmac_f32_e32 v139, 0x3f317217, v138
	v_sub_f32_e32 v124, v121, v123
	v_sub_f32_e32 v140, v137, v139
	s_waitcnt lgkmcnt(8)
	v_fma_f32 v144, v124, s57, v128
	v_sub_f32_e32 v127, v130, v129
	v_add_f32_e32 v145, v129, v134
	v_fma_f32 v128, v140, s57, v144
	v_sub_f32_e32 v143, v130, v145
	v_add_f32_e32 v129, v145, v135
	v_mul_f32_e32 v132, 0x3fb8aa3b, v144
	v_mul_f32_e32 v133, 0x3fb8aa3b, v128
	v_exp_f32_e32 v125, v132
	v_exp_f32_e32 v141, v133
	v_exp_f32_e64 v126, -v132
	v_exp_f32_e64 v142, -v133
	v_mul_f32_e32 v132, 0x3fb8aa3b, v127
	v_mul_f32_e32 v133, 0x3fb8aa3b, v143
	v_mul_f32_e32 v125, v125, v72
	v_mul_f32_e32 v141, v141, v73
	v_mul_f32_e32 v126, v126, v80
	v_mul_f32_e32 v142, v142, v81
	v_cvt_pk_bf16_f32 v125, v125, v1
	v_cvt_pk_bf16_f32 v141, v141, v1
	v_cvt_pk_bf16_f32 v126, v126, v1
	v_cvt_pk_bf16_f32 v142, v142, v1
	global_store_short v42, v125, s[46:47]
	global_store_short v43, v141, s[46:47]
	global_store_short v42, v126, s[46:47] offset:1024
	global_store_short v43, v142, s[46:47] offset:1024
	v_exp_f32_e32 v120, v132
	v_exp_f32_e32 v136, v133
	v_exp_f32_e64 v121, -v132
	v_exp_f32_e64 v137, -v133
	v_nop
	v_nop
	v_nop
	v_nop
	v_mul_f32_e32 v120, v120, v72
	v_mul_f32_e32 v136, v136, v73
	v_mul_f32_e32 v121, v121, v80
	v_mul_f32_e32 v137, v137, v81
	v_cvt_pk_bf16_f32 v120, v120, v1
	v_cvt_pk_bf16_f32 v136, v136, v1
	v_cvt_pk_bf16_f32 v121, v121, v1
	v_cvt_pk_bf16_f32 v137, v137, v1
	global_store_short v46, v120, s[48:49]
	global_store_short v46, v136, s[48:49] offset:1024
	global_store_short v46, v121, s[50:51]
	global_store_short v46, v137, s[50:51] offset:1024
	s_waitcnt lgkmcnt(0)
; #define LAS __attribute__((address_space(3)))
; DI float bf2f(bf16_t v) { return __uint_as_float(((unsigned)v) << 16); }
; DI bf16_t f2bf(float f) { return (bf16_t)(cvt_pk(f, 0.f) & 0xffffu); }
; DI float logsig16(float z) { return (fminf(z, 0.f) - __logf(1.0f + __expf(-fabsf(z)))) * (1.0f / 16.0f); }
; DI void gla_gate_phase(const Params& P, LAS unsigned char* lds, int lj) {
;     ...
;       for (int ii = 0; ii < 16; ++ii) {
;         const int i = ib * 16 + ii;
;         float z = bf_;
; #pragma unroll
;         for (int j4 = 0; j4 < 4; ++j4) { const f32x4 zz = *(const LAS f32x4*)(zL + i * 32 + j4 * 4); z += zz[0] * wf[j4 * 4] + zz[1] * wf[j4 * 4 + 1] + zz[2] * wf[j4 * 4 + 2] + zz[3] * wf[j4 * 4 + 3]; }
;         runf += logsig16(z);
;         const float Bi = totb - runb; runb += lsb[i];
;         const size_t tokrow = (size_t)item * 64 + i;
;         bf16_t* pr = proj + tokrow * 3072 + col;
;         const float q = bf2f(qraw[ii]), k = bf2f(kraw[ii]);
;         pr[0] = f2bf(q * __expf(runf)); pr[512] = f2bf(k * __expf(-runf));
;         QB[tokrow * 512 + col] = f2bf(q * __expf(Bi)); KB[tokrow * 512 + col] = f2bf(k * __expf(-Bi));
;       }
;       asm volatile("" ::: "memory");
;     }
;     dect[(size_t)item * 512 + col] = __expf(runf);
;     dect[(size_t)(512 + item) * 512 + col] = __expf(totb);
;   }
	ds_read_b32 v134, v50 offset:12288
	ds_read_b32 v135, v50 offset:14336
	v_mul_f32_e32 v120, v3, v85
	v_mul_f32_e32 v136, v3, v101
	v_fmac_f32_e32 v120, v2, v84
	v_fmac_f32_e32 v136, v2, v100
	v_fmac_f32_e32 v120, v4, v86
	v_fmac_f32_e32 v136, v4, v102
	v_fmac_f32_e32 v120, v5, v87
	v_fmac_f32_e32 v136, v5, v103
	v_add_f32_e32 v124, v34, v120
	v_add_f32_e32 v140, v34, v136
	v_mul_f32_e32 v120, v7, v89
	v_mul_f32_e32 v136, v7, v105
	v_fmac_f32_e32 v120, v6, v88
	v_fmac_f32_e32 v136, v6, v104
	v_fmac_f32_e32 v120, v8, v90
	v_fmac_f32_e32 v136, v8, v106
	v_fmac_f32_e32 v120, v9, v91
	v_fmac_f32_e32 v136, v9, v107
	v_add_f32_e32 v124, v124, v120
	v_add_f32_e32 v140, v140, v136
	v_mul_f32_e32 v120, v11, v93
	v_mul_f32_e32 v136, v11, v109
	v_fmac_f32_e32 v120, v10, v92
	v_fmac_f32_e32 v136, v10, v108
	v_fmac_f32_e32 v120, v12, v94
	v_fmac_f32_e32 v136, v12, v110
	v_fmac_f32_e32 v120, v13, v95
	v_fmac_f32_e32 v136, v13, v111
	v_add_f32_e32 v124, v124, v120
	v_add_f32_e32 v140, v140, v136
	v_mul_f32_e32 v120, v15, v97
	v_mul_f32_e32 v136, v15, v113
	v_fmac_f32_e32 v120, v14, v96
	v_fmac_f32_e32 v136, v14, v112
	v_fmac_f32_e32 v120, v16, v98
	v_fmac_f32_e32 v136, v16, v114
	v_fmac_f32_e32 v120, v17, v99
	v_fmac_f32_e32 v136, v17, v115
	v_add_f32_e32 v124, v124, v120
	v_add_f32_e32 v140, v140, v136
	v_add_u32_e32 v49, 0x400, v49
	ds_read_b128 v[84:87], v49 offset:0
	ds_read_b128 v[88:91], v49 offset:16
	ds_read_b128 v[92:95], v49 offset:32
	ds_read_b128 v[96:99], v49 offset:48
	ds_read_b128 v[100:103], v49 offset:128
	ds_read_b128 v[104:107], v49 offset:144
	ds_read_b128 v[108:111], v49 offset:160
	ds_read_b128 v[112:115], v49 offset:176
	v_min_f32_e32 v121, 0, v124
	v_min_f32_e32 v137, 0, v140
	v_mul_f32_e64 v122, |v124|, s16
	v_mul_f32_e64 v138, |v140|, s16
	v_exp_f32_e32 v122, v122
	v_exp_f32_e32 v138, v138
	v_add_f32_e32 v122, 1.0, v122
	v_add_f32_e32 v138, 1.0, v138
	v_log_f32_e32 v122, v122
	v_log_f32_e32 v138, v138
	v_mul_f32_e32 v123, 0x3f317217, v122
	v_mul_f32_e32 v139, 0x3f317217, v138
	v_fma_f32 v123, v122, s55, -v123
	v_fma_f32 v139, v138, s55, -v139
	v_fmac_f32_e32 v123, 0x3377d1cf, v122
	v_fmac_f32_e32 v139, 0x3377d1cf, v138
	v_fmac_f32_e32 v123, 0x3f317217, v122
	v_fmac_f32_e32 v139, 0x3f317217, v138
	v_sub_f32_e32 v124, v121, v123
	v_sub_f32_e32 v140, v137, v139
	s_waitcnt lgkmcnt(8)
	v_fma_f32 v144, v124, s57, v128
	v_sub_f32_e32 v127, v130, v129
	v_add_f32_e32 v145, v129, v134
	v_fma_f32 v128, v140, s57, v144
	v_sub_f32_e32 v143, v130, v145
	v_add_f32_e32 v129, v145, v135
	v_mul_f32_e32 v132, 0x3fb8aa3b, v144
	v_mul_f32_e32 v133, 0x3fb8aa3b, v128
	v_exp_f32_e32 v125, v132
	v_exp_f32_e32 v141, v133
	v_exp_f32_e64 v126, -v132
	v_exp_f32_e64 v142, -v133
	v_mul_f32_e32 v132, 0x3fb8aa3b, v127
	v_mul_f32_e32 v133, 0x3fb8aa3b, v143
	v_mul_f32_e32 v125, v125, v74
	v_mul_f32_e32 v141, v141, v75
	v_mul_f32_e32 v126, v126, v82
	v_mul_f32_e32 v142, v142, v83
	v_cvt_pk_bf16_f32 v125, v125, v1
	v_cvt_pk_bf16_f32 v141, v141, v1
	v_cvt_pk_bf16_f32 v126, v126, v1
	v_cvt_pk_bf16_f32 v142, v142, v1
	global_store_short v44, v125, s[46:47]
	global_store_short v45, v141, s[46:47]
	global_store_short v44, v126, s[46:47] offset:1024
	global_store_short v45, v142, s[46:47] offset:1024
	v_exp_f32_e32 v120, v132
	v_exp_f32_e32 v136, v133
	v_exp_f32_e64 v121, -v132
	v_exp_f32_e64 v137, -v133
	v_nop
	v_nop
	v_nop
	v_nop
	v_mul_f32_e32 v120, v120, v74
	v_mul_f32_e32 v136, v136, v75
	v_mul_f32_e32 v121, v121, v82
	v_mul_f32_e32 v137, v137, v83
	v_cvt_pk_bf16_f32 v120, v120, v1
	v_cvt_pk_bf16_f32 v136, v136, v1
	v_cvt_pk_bf16_f32 v121, v121, v1
	v_cvt_pk_bf16_f32 v137, v137, v1
	global_store_short v46, v120, s[48:49] offset:2048
	global_store_short v46, v136, s[48:49] offset:3072
	global_store_short v46, v121, s[50:51] offset:2048
	global_store_short v46, v137, s[50:51] offset:3072
	v_add_u32_e32 v50, 0x4000, v50
	s_add_u32 s46, s46, 0xc000
	s_addc_u32 s47, s47, 0
	s_add_u32 s48, s48, 0x2000
	s_addc_u32 s49, s49, 0
	s_add_u32 s50, s50, 0x2000
	s_addc_u32 s51, s51, 0
	s_add_i32 s43, s43, 1
	s_cmp_lt_u32 s43, 8
	s_cbranch_scc1 .Lgt_main
	s_lshl_b32 s0, s42, 11
	s_add_u32 s0, s6, s0
	s_addc_u32 s1, s7, 0
	s_add_u32 s0, s0, 0xe00000
	s_addc_u32 s1, s1, 0
	v_mul_f32_e32 v120, 0x3fb8aa3b, v128
	v_mul_f32_e32 v136, 0x3fb8aa3b, v130
	v_exp_f32_e32 v120, v120
	v_exp_f32_e32 v136, v136
	s_nop 1
	global_store_dword v36, v120, s[0:1]
	s_add_u32 s0, s0, 0x100000
	s_addc_u32 s1, s1, 0
	global_store_dword v36, v136, s[0:1]
	s_add_i32 s42, s42, s10
	s_cmpk_lt_i32 s42, 0x200
	s_cbranch_scc1 .Lgt_item
